# attention tiles: the per-wave serial s_ff1/v_readlane OR-reduction loops of the selected-block union mask replaced by direct LDS ds_or from every active lane; on top of version 46
# speedup vs baseline: 1.0281x; 1.0104x over previous
.LBB0_1417:
	v_cmp_gt_u32_e32 vcc, 16, v162
	s_and_b64 s[8:9], vcc, s[0:1]
	s_and_saveexec_b64 s[0:1], s[8:9]
	s_cbranch_execz .LBB0_1434
	s_add_i32 s12, 0, 0x12400
	v_mov_b32_e32 v1, s12
	v_readlane_b32 s12, v240, 44
	v_readlane_b32 s13, v240, 45
	v_readlane_b32 s8, v240, 46
	ds_or_b32 v1, v26
	v_mov_b32_e32 v30, s12
	ds_or_b32 v30, v27
	v_mov_b32_e32 v1, s13
	ds_or_b32 v1, v28
	v_mov_b32_e32 v30, s8
	ds_or_b32 v30, v29

.LBB0_1540:
	v_cmp_gt_u32_e32 vcc, 16, v177
	s_and_b64 s[8:9], vcc, s[0:1]
	s_and_saveexec_b64 s[0:1], s[8:9]
	s_cbranch_execz .LBB0_1557
	s_add_i32 s14, 0, 0x12400
	v_mov_b32_e32 v1, s14
	v_readlane_b32 s14, v240, 44
	v_readlane_b32 s15, v240, 45
	v_readlane_b32 s8, v240, 46
	ds_or_b32 v1, v18
	v_mov_b32_e32 v22, s14
	ds_or_b32 v22, v19
	v_mov_b32_e32 v1, s15
	ds_or_b32 v1, v20
	v_mov_b32_e32 v22, s8
	ds_or_b32 v22, v21
